# NATTEN fixed-shift loops: QK K-fragment LDS reads pipelined four ahead through spare registers with counted lgkmcnt (was one buffer: every MFMA behind a full LDS round trip)
# baseline (speedup 1.0000x reference)
.LBB0_1107:
	s_add_i32 s34, s36, 2
	s_bitcmp1_b32 s36, 0
	s_cselect_b64 s[2:3], -1, 0
	s_and_b64 s[6:7], s[2:3], exec
	s_cselect_b32 s6, 0x3400, 0
	s_add_u32 s66, s36, 1
	v_add_u32_e32 v146, s6, v204
	s_addc_u32 s67, s37, 0
	s_andn2_b32 s6, 1, s36
	s_mulk_i32 s6, 0x2400
	s_waitcnt vmcnt(0)
	ds_write_b128 v146, v[130:133]
	v_add_u32_e32 v130, s6, v203
	ds_write_b128 v130, v[134:137] offset:26624
	s_add_i32 s6, s36, 3
	v_add_u32_e32 v134, s36, v174
	v_lshl_add_u64 v[178:179], v[164:165], 0, s[36:37]
	v_add_u32_e32 v132, 3, v134
	v_lshl_add_u64 v[130:131], v[178:179], 0, 3
	v_cmp_lt_i32_e32 vcc, s6, v201
	v_add_u32_e32 v136, 2, v134
	v_lshl_add_u64 v[134:135], v[178:179], 0, 2
	v_cndmask_b32_e32 v133, 0, v131, vcc
	v_cndmask_b32_e32 v132, v132, v130, vcc
	v_cndmask_b32_e32 v131, v145, v139, vcc
	v_cndmask_b32_e32 v130, v144, v138, vcc
	v_cmp_lt_i32_e32 vcc, s34, v201
	v_mad_u64_u32 v[130:131], s[6:7], v132, s74, v[130:131]
	s_nop 0
	v_cndmask_b32_e32 v137, 0, v135, vcc
	v_cndmask_b32_e32 v136, v136, v134, vcc
	v_cndmask_b32_e32 v135, v163, v141, vcc
	v_cndmask_b32_e32 v134, v162, v140, vcc
	v_mad_u64_u32 v[134:135], s[6:7], v136, s74, v[134:135]
	v_mov_b32_e32 v132, v131
	v_mov_b32_e32 v136, v135
	v_mad_u64_u32 v[132:133], s[6:7], v133, s74, v[132:133]
	v_mad_u64_u32 v[136:137], s[6:7], v137, s74, v[136:137]
	v_mov_b32_e32 v131, v132
	v_mov_b32_e32 v135, v136
	v_lshl_add_u64 v[130:131], v[168:169], 1, v[130:131]
	v_lshl_add_u64 v[134:135], v[172:173], 1, v[134:135]
	v_lshl_add_u64 v[130:131], v[170:171], 1, v[130:131]
	v_lshl_add_u64 v[134:135], v[134:135], 0, v[112:113]
	global_load_dwordx4 v[130:133], v[130:131], off
	v_cmp_lt_i32_e32 vcc, s66, v142
	global_load_dwordx4 v[134:137], v[134:135], off
	s_and_saveexec_b64 s[68:69], vcc
	s_cbranch_execz .LBB0_1113
	v_cmp_ge_i32_e64 s[70:71], s66, v201
	v_cmp_lt_i32_e32 vcc, s66, v201
	s_and_saveexec_b64 s[72:73], vcc
	v_add_u32_e32 v146, 1, v178
	v_cmp_ge_u32_e32 vcc, v146, v205
	v_cmp_lt_u32_e64 s[6:7], v146, v206
	s_and_b64 s[6:7], vcc, s[6:7]
	s_andn2_b64 s[70:71], s[70:71], exec
	s_and_b64 s[6:7], s[6:7], exec
	s_or_b64 s[70:71], s[70:71], s[6:7]
	s_or_b64 exec, exec, s[72:73]
	s_and_saveexec_b64 s[6:7], s[70:71]
	s_cbranch_execz .LBB0_1112
	s_bitcmp1_b32 s66, 0
	s_cselect_b32 s34, 0x3400, 0
	v_add_u32_e32 v150, s34, v216
	ds_read_b128 v[64:67], v150
	ds_read_b128 v[146:149], v150 offset:4608
	ds_read_b128 v[230:233], v150 offset:32
	ds_read_b128 v[234:237], v150 offset:4640
	ds_read_b128 v[238:241], v150 offset:64
	s_waitcnt lgkmcnt(3)
	v_mfma_f32_32x32x16_bf16 v[48:63], v[64:67], v[114:117], v[16:31]
	v_mfma_f32_32x32x16_bf16 v[64:79], v[146:149], v[114:117], v[16:31]
	ds_read_b128 v[146:149], v150 offset:4672
	s_waitcnt lgkmcnt(3)
	v_mfma_f32_32x32x16_bf16 v[48:63], v[230:233], v[118:121], v[48:63]
	ds_read_b128 v[230:233], v150 offset:96
	s_waitcnt lgkmcnt(3)
	v_mfma_f32_32x32x16_bf16 v[64:79], v[234:237], v[118:121], v[64:79]
	ds_read_b128 v[234:237], v150 offset:4704
	s_waitcnt lgkmcnt(3)
	v_mfma_f32_32x32x16_bf16 v[48:63], v[238:241], v[122:125], v[48:63]
	s_waitcnt lgkmcnt(2)
	v_mfma_f32_32x32x16_bf16 v[64:79], v[146:149], v[122:125], v[64:79]
	s_waitcnt lgkmcnt(1)
	v_mfma_f32_32x32x16_bf16 v[48:63], v[230:233], v[126:129], v[48:63]
	s_waitcnt lgkmcnt(0)
	v_mfma_f32_32x32x16_bf16 v[64:79], v[234:237], v[126:129], v[64:79]

.LBB0_1132:
	v_cmp_ge_i32_e64 s[8:9], v183, v201
	v_cmp_lt_i32_e32 vcc, v183, v201
	s_and_saveexec_b64 s[36:37], vcc
	v_add3_u32 v146, v164, s68, -2
	v_cmp_ge_u32_e32 vcc, v146, v205
	v_cmp_lt_u32_e64 s[6:7], v146, v206
	s_and_b64 s[6:7], vcc, s[6:7]
	s_andn2_b64 s[8:9], s[8:9], exec
	s_and_b64 s[6:7], s[6:7], exec
	s_or_b64 s[8:9], s[8:9], s[6:7]
	s_or_b64 exec, exec, s[36:37]
	s_and_saveexec_b64 s[6:7], s[8:9]
	s_cbranch_execz .LBB0_1136
	v_and_b32_e32 v48, 1, v183
	v_cmp_eq_u32_e32 vcc, 1, v48
	s_nop 1
	v_cndmask_b32_e32 v48, 0, v197, vcc
	v_add_u32_e32 v150, v216, v48
	ds_read_b128 v[64:67], v150
	ds_read_b128 v[146:149], v150 offset:4608
	ds_read_b128 v[230:233], v150 offset:32
	ds_read_b128 v[234:237], v150 offset:4640
	ds_read_b128 v[238:241], v150 offset:64
	s_waitcnt lgkmcnt(3)
	v_mfma_f32_32x32x16_bf16 v[48:63], v[64:67], v[114:117], v[16:31]
	v_mfma_f32_32x32x16_bf16 v[64:79], v[146:149], v[114:117], v[16:31]
	ds_read_b128 v[146:149], v150 offset:4672
	s_waitcnt lgkmcnt(3)
	v_mfma_f32_32x32x16_bf16 v[48:63], v[230:233], v[118:121], v[48:63]
	ds_read_b128 v[230:233], v150 offset:96
	s_waitcnt lgkmcnt(3)
	v_mfma_f32_32x32x16_bf16 v[64:79], v[234:237], v[118:121], v[64:79]
	ds_read_b128 v[234:237], v150 offset:4704
	s_waitcnt lgkmcnt(3)
	v_mfma_f32_32x32x16_bf16 v[48:63], v[238:241], v[122:125], v[48:63]
	s_waitcnt lgkmcnt(2)
	v_mfma_f32_32x32x16_bf16 v[64:79], v[146:149], v[122:125], v[64:79]
	s_waitcnt lgkmcnt(1)
	v_mfma_f32_32x32x16_bf16 v[48:63], v[230:233], v[126:129], v[48:63]
	s_waitcnt lgkmcnt(0)
	v_mfma_f32_32x32x16_bf16 v[64:79], v[234:237], v[126:129], v[64:79]
